# speedup vs baseline: 1.0272x; 1.0095x over previous
.LBB0_345:
	v_lshl_add_u32 v144, s8, 8, v152
	v_lshlrev_b32_e32 v232, 2, v144
	global_load_dword v233, v232, s[66:67]
	global_load_dword v234, v232, s[66:67] offset:64
	global_load_dword v235, v232, s[66:67] offset:128
	global_load_dword v236, v232, s[66:67] offset:192
	global_load_dword v237, v232, s[66:67] offset:512
	global_load_dword v238, v232, s[66:67] offset:576
	global_load_dword v239, v232, s[66:67] offset:640
	global_load_dword v240, v232, s[66:67] offset:704
	v_ashrrev_i32_e32 v145, 31, v144
	v_lshl_add_u64 v[142:143], v[144:145], 2, s[66:67]
	s_nop 0
	v_lshl_or_b32 v142, s6, 8, v154
	v_mul_hi_i32 v143, v142, s74
	v_lshlrev_b64 v[146:147], 8, v[144:145]
	v_lshrrev_b32_e32 v145, 31, v143
	v_lshrrev_b32_e32 v143, 5, v143
	v_add_u32_e32 v143, v143, v145
	v_mul_lo_u32 v143, v143, s47
	v_sub_u32_e32 v143, v142, v143
	v_cmp_lt_i32_e32 vcc, s82, v143
	v_add_u32_e32 v143, 0xffffff80, v143
	v_lshl_add_u64 v[146:147], s[16:17], 0, v[146:147]
	s_waitcnt vmcnt(0)
	v_mov_b32_e32 v132, v233
	v_mbcnt_lo_u32_b32 v252, -1, 0
	v_mbcnt_hi_u32_b32 v252, -1, v252
	v_and_b32_e32 v252, 16, v252
	v_lshrrev_b32_e32 v253, 1, v252
	v_add_u32_e32 v252, v252, v253
	v_mov_b32_e32 v253, 0
	v_mul_f32_e32 v148, 0x3dd53b94, v132
	v_pk_mul_f32 v[126:127], v[126:127], v[148:149] op_sel_hi:[1,0]
	v_pk_mul_f32 v[124:125], v[124:125], v[148:149] op_sel_hi:[1,0]
	v_lshrrev_b32_e32 v132, 1, v143
	s_and_saveexec_b64 s[6:7], vcc
	s_cbranch_execz .LBB0_347
	v_lshl_add_u64 v[150:151], v[132:133], 3, v[146:147]
	global_load_dwordx4 v[158:161], v[150:151], off
	s_waitcnt vmcnt(0)
	v_pk_mul_f32 v[162:163], v[124:125], v[158:159] op_sel:[1,1] op_sel_hi:[0,1]
	v_mul_f32_e32 v164, v127, v161
	v_mul_f32_e32 v166, v126, v161
	v_pk_mul_f32 v[150:151], v[124:125], v[158:159]
	v_pk_fma_f32 v[124:125], v[124:125], v[158:159], v[162:163] op_sel_hi:[1,0,1]
	v_pk_fma_f32 v[158:159], v[126:127], v[160:161], v[164:165] op_sel_hi:[1,1,0] neg_lo:[0,0,1] neg_hi:[0,0,1]
	v_pk_fma_f32 v[160:161], v[126:127], v[160:161], v[166:167] op_sel:[1,0,0] op_sel_hi:[0,1,0]
	v_sub_f32_e32 v124, v150, v162
	v_mov_b32_e32 v126, v158
	v_mov_b32_e32 v127, v160
.LBB0_347:
	s_or_b64 exec, exec, s[6:7]
	v_cvt_pk_bf16_f32 v244, v124, v125
	v_mov_b64_e32 v[124:125], s[64:65]
	v_mad_i64_i32 v[124:125], s[6:7], v144, s83, v[124:125]
	v_ashrrev_i32_e32 v143, 31, v142
	v_mov_b32_e32 v149, v148
	v_cvt_pk_bf16_f32 v245, v126, v127
	v_lshl_add_u64 v[124:125], v[142:143], 1, v[124:125]
	v_mov_b32_e32 v126, v148
	v_mov_b32_e32 v127, v148
	s_nop 0
	v_pk_mul_f32 v[150:151], v[122:123], v[126:127]
	v_pk_mul_f32 v[122:123], v[120:121], v[148:149]
	v_or_b32_e32 v120, 16, v142
	v_mul_hi_i32 v121, v120, s74
	v_lshrrev_b32_e32 v145, 31, v121
	v_lshrrev_b32_e32 v121, 5, v121
	v_add_u32_e32 v121, v121, v145
	v_mul_lo_u32 v121, v121, s47
	v_sub_u32_e32 v120, v120, v121
	v_cmp_lt_i32_e64 s[6:7], s82, v120
	v_add_u32_e32 v120, 0xffffff80, v120
	v_lshrrev_b32_e32 v120, 1, v120
	s_and_saveexec_b64 s[8:9], s[6:7]
	s_cbranch_execz .LBB0_349
	v_mov_b32_e32 v121, v133
	v_lshl_add_u64 v[158:159], v[120:121], 3, v[146:147]
	global_load_dwordx4 v[158:161], v[158:159], off
	s_waitcnt vmcnt(0)
	v_pk_mul_f32 v[164:165], v[122:123], v[158:159] op_sel:[1,1] op_sel_hi:[0,1]
	v_mul_f32_e32 v166, v151, v161
	v_mul_f32_e32 v168, v150, v161
	v_pk_mul_f32 v[162:163], v[122:123], v[158:159]
	v_pk_fma_f32 v[122:123], v[122:123], v[158:159], v[164:165] op_sel_hi:[1,0,1]
	v_pk_fma_f32 v[158:159], v[150:151], v[160:161], v[166:167] op_sel_hi:[1,1,0] neg_lo:[0,0,1] neg_hi:[0,0,1]
	v_pk_fma_f32 v[160:161], v[150:151], v[160:161], v[168:169] op_sel:[1,0,0] op_sel_hi:[0,1,0]
	v_sub_f32_e32 v122, v162, v164
	v_mov_b32_e32 v150, v158
	v_mov_b32_e32 v151, v160
.LBB0_349:
	s_or_b64 exec, exec, s[8:9]
	v_cvt_pk_bf16_f32 v246, v122, v123
	v_cvt_pk_bf16_f32 v247, v150, v151
	v_or_b32_e32 v121, 0x80, v142
	s_nop 1
	v_permlane16_swap_b32_e32 v244, v246
	v_permlane16_swap_b32_e32 v245, v247
	v_lshl_add_u64 v[242:243], v[124:125], 0, v[252:253]
	global_store_dwordx4 v[242:243], v[244:247], off sc0 sc1
	v_pk_mul_f32 v[122:123], v[118:119], v[126:127]
	v_pk_mul_f32 v[118:119], v[116:117], v[148:149]
	v_mul_hi_i32 v116, v121, s74
	v_lshrrev_b32_e32 v117, 31, v116
	v_lshrrev_b32_e32 v116, 5, v116
	v_add_u32_e32 v116, v116, v117
	v_mul_lo_u32 v116, v116, s47
	v_sub_u32_e32 v116, v121, v116
	v_cmp_lt_i32_e64 s[8:9], s82, v116
	v_add_u32_e32 v116, 0xffffff80, v116
	v_lshrrev_b32_e32 v116, 1, v116
	s_and_saveexec_b64 s[10:11], s[8:9]
	s_cbranch_execz .LBB0_351
	v_mov_b32_e32 v117, v133
	v_lshl_add_u64 v[126:127], v[116:117], 3, v[146:147]
	global_load_dwordx4 v[158:161], v[126:127], off
	s_waitcnt vmcnt(0)
	v_pk_mul_f32 v[150:151], v[118:119], v[158:159] op_sel:[1,1] op_sel_hi:[0,1]
	v_mul_f32_e32 v162, v123, v161
	v_mul_f32_e32 v164, v122, v161
	v_pk_mul_f32 v[126:127], v[118:119], v[158:159]
	v_pk_fma_f32 v[118:119], v[118:119], v[158:159], v[150:151] op_sel_hi:[1,0,1]
	v_pk_fma_f32 v[158:159], v[122:123], v[160:161], v[162:163] op_sel_hi:[1,1,0] neg_lo:[0,0,1] neg_hi:[0,0,1]
	v_pk_fma_f32 v[160:161], v[122:123], v[160:161], v[164:165] op_sel:[1,0,0] op_sel_hi:[0,1,0]
	v_sub_f32_e32 v118, v126, v150
	v_mov_b32_e32 v122, v158
	v_mov_b32_e32 v123, v160
.LBB0_351:
	s_or_b64 exec, exec, s[10:11]
	v_cvt_pk_bf16_f32 v248, v118, v119
	v_cvt_pk_bf16_f32 v249, v122, v123
	s_nop 0
	v_mov_b32_e32 v118, v148
	v_mov_b32_e32 v119, v148
	v_pk_mul_f32 v[118:119], v[114:115], v[118:119]
	v_pk_mul_f32 v[114:115], v[112:113], v[148:149]
	v_or_b32_e32 v112, 0x90, v142
	v_mul_hi_i32 v113, v112, s74
	v_lshrrev_b32_e32 v117, 31, v113
	v_lshrrev_b32_e32 v113, 5, v113
	v_add_u32_e32 v113, v113, v117
	v_mul_lo_u32 v113, v113, s47
	v_sub_u32_e32 v112, v112, v113
	v_cmp_lt_i32_e64 s[10:11], s82, v112
	v_add_u32_e32 v112, 0xffffff80, v112
	v_lshrrev_b32_e32 v112, 1, v112
	s_and_saveexec_b64 s[36:37], s[10:11]
	s_cbranch_execz .LBB0_353
	v_mov_b32_e32 v113, v133
	v_lshl_add_u64 v[122:123], v[112:113], 3, v[146:147]
	global_load_dwordx4 v[146:149], v[122:123], off
	s_waitcnt vmcnt(0)
	v_pk_mul_f32 v[126:127], v[114:115], v[146:147] op_sel:[1,1] op_sel_hi:[0,1]
	v_mul_f32_e32 v150, v119, v149
	v_mul_f32_e32 v158, v118, v149
	v_pk_mul_f32 v[122:123], v[114:115], v[146:147]
	v_pk_fma_f32 v[114:115], v[114:115], v[146:147], v[126:127] op_sel_hi:[1,0,1]
	v_pk_fma_f32 v[146:147], v[118:119], v[148:149], v[150:151] op_sel_hi:[1,1,0] neg_lo:[0,0,1] neg_hi:[0,0,1]
	v_pk_fma_f32 v[148:149], v[118:119], v[148:149], v[158:159] op_sel:[1,0,0] op_sel_hi:[0,1,0]
	v_sub_f32_e32 v114, v122, v126
	v_mov_b32_e32 v118, v146
	v_mov_b32_e32 v119, v148
.LBB0_353:
	s_or_b64 exec, exec, s[36:37]
	v_cvt_pk_bf16_f32 v250, v114, v115
	v_cvt_pk_bf16_f32 v251, v118, v119
	v_or_b32_e32 v118, 16, v144
	v_ashrrev_i32_e32 v119, 31, v118
	s_nop 1
	v_permlane16_swap_b32_e32 v248, v250
	v_permlane16_swap_b32_e32 v249, v251
	v_lshl_add_u64 v[242:243], v[124:125], 0, v[252:253]
	global_store_dwordx4 v[242:243], v[248:251], off offset:256 sc0 sc1
	v_lshl_add_u64 v[114:115], v[118:119], 2, s[66:67]
	v_mov_b32_e32 v113, v234
	v_lshlrev_b64 v[124:125], 8, v[118:119]
	v_mul_f32_e32 v114, 0x3dd53b94, v113
	v_pk_mul_f32 v[122:123], v[110:111], v[114:115] op_sel_hi:[1,0]
	v_pk_mul_f32 v[110:111], v[108:109], v[114:115] op_sel_hi:[1,0]
	v_lshl_add_u64 v[108:109], s[16:17], 0, v[124:125]
	s_and_saveexec_b64 s[36:37], vcc
	s_cbranch_execz .LBB0_355
	v_lshl_add_u64 v[124:125], v[132:133], 3, v[108:109]
	global_load_dwordx4 v[124:127], v[124:125], off
	s_waitcnt vmcnt(0)
	v_pk_mul_f32 v[148:149], v[110:111], v[124:125] op_sel:[1,1] op_sel_hi:[0,1]
	v_mul_f32_e32 v150, v123, v127
	v_mul_f32_e32 v158, v122, v127
	v_pk_mul_f32 v[146:147], v[110:111], v[124:125]
	v_pk_fma_f32 v[110:111], v[110:111], v[124:125], v[148:149] op_sel_hi:[1,0,1]
	v_pk_fma_f32 v[124:125], v[122:123], v[126:127], v[150:151] op_sel_hi:[1,1,0] neg_lo:[0,0,1] neg_hi:[0,0,1]
	v_pk_fma_f32 v[126:127], v[122:123], v[126:127], v[158:159] op_sel:[1,0,0] op_sel_hi:[0,1,0]
	v_sub_f32_e32 v110, v146, v148
	v_mov_b32_e32 v122, v124
	v_mov_b32_e32 v123, v126
.LBB0_355:
	s_or_b64 exec, exec, s[36:37]
	v_cvt_pk_bf16_f32 v244, v110, v111
	v_mov_b64_e32 v[110:111], s[64:65]
	v_mov_b32_e32 v115, v114
	v_mad_i64_i32 v[110:111], s[12:13], v118, s83, v[110:111]
	v_mov_b32_e32 v118, v114
	v_mov_b32_e32 v119, v114
	v_lshl_add_u64 v[110:111], v[142:143], 1, v[110:111]
	v_pk_mul_f32 v[106:107], v[106:107], v[118:119]
	v_pk_mul_f32 v[104:105], v[104:105], v[114:115]
	v_cvt_pk_bf16_f32 v245, v122, v123
	s_nop 0
	s_and_saveexec_b64 s[36:37], s[6:7]
	s_cbranch_execz .LBB0_357
	v_mov_b32_e32 v121, v133
	v_lshl_add_u64 v[122:123], v[120:121], 3, v[108:109]
	global_load_dwordx4 v[122:125], v[122:123], off
	s_waitcnt vmcnt(0)
	v_pk_mul_f32 v[146:147], v[104:105], v[122:123] op_sel:[1,1] op_sel_hi:[0,1]
	v_mul_f32_e32 v148, v107, v125
	v_mul_f32_e32 v150, v106, v125
	v_pk_mul_f32 v[126:127], v[104:105], v[122:123]
	v_pk_fma_f32 v[104:105], v[104:105], v[122:123], v[146:147] op_sel_hi:[1,0,1]
	v_pk_fma_f32 v[122:123], v[106:107], v[124:125], v[148:149] op_sel_hi:[1,1,0] neg_lo:[0,0,1] neg_hi:[0,0,1]
	v_pk_fma_f32 v[124:125], v[106:107], v[124:125], v[150:151] op_sel:[1,0,0] op_sel_hi:[0,1,0]
	v_sub_f32_e32 v104, v126, v146
	v_mov_b32_e32 v106, v122
	v_mov_b32_e32 v107, v124
.LBB0_357:
	s_or_b64 exec, exec, s[36:37]
	v_pk_mul_f32 v[102:103], v[102:103], v[118:119]
	v_pk_mul_f32 v[100:101], v[100:101], v[114:115]
	v_cvt_pk_bf16_f32 v246, v104, v105
	v_cvt_pk_bf16_f32 v247, v106, v107
	s_nop 1
	v_permlane16_swap_b32_e32 v244, v246
	v_permlane16_swap_b32_e32 v245, v247
	v_lshl_add_u64 v[242:243], v[110:111], 0, v[252:253]
	global_store_dwordx4 v[242:243], v[244:247], off sc0 sc1
	s_and_saveexec_b64 s[36:37], s[8:9]
	s_cbranch_execz .LBB0_359
	v_mov_b32_e32 v117, v133
	v_lshl_add_u64 v[104:105], v[116:117], 3, v[108:109]
	global_load_dwordx4 v[104:107], v[104:105], off
	s_waitcnt vmcnt(0)
	v_pk_mul_f32 v[122:123], v[100:101], v[104:105] op_sel:[1,1] op_sel_hi:[0,1]
	v_mul_f32_e32 v124, v103, v107
	v_mul_f32_e32 v126, v102, v107
	v_pk_mul_f32 v[118:119], v[100:101], v[104:105]
	v_pk_fma_f32 v[100:101], v[100:101], v[104:105], v[122:123] op_sel_hi:[1,0,1]
	v_pk_fma_f32 v[104:105], v[102:103], v[106:107], v[124:125] op_sel_hi:[1,1,0] neg_lo:[0,0,1] neg_hi:[0,0,1]
	v_pk_fma_f32 v[106:107], v[102:103], v[106:107], v[126:127] op_sel:[1,0,0] op_sel_hi:[0,1,0]
	v_sub_f32_e32 v100, v118, v122
	v_mov_b32_e32 v102, v104
	v_mov_b32_e32 v103, v106
.LBB0_359:
	s_or_b64 exec, exec, s[36:37]
	v_cvt_pk_bf16_f32 v248, v100, v101
	v_cvt_pk_bf16_f32 v249, v102, v103
	s_nop 0
	v_mov_b32_e32 v100, v114
	v_mov_b32_e32 v101, v114
	v_pk_mul_f32 v[98:99], v[98:99], v[100:101]
	v_pk_mul_f32 v[96:97], v[96:97], v[114:115]
	s_and_saveexec_b64 s[36:37], s[10:11]
	s_cbranch_execz .LBB0_361
	v_mov_b32_e32 v113, v133
	v_lshl_add_u64 v[100:101], v[112:113], 3, v[108:109]
	global_load_dwordx4 v[100:103], v[100:101], off
	s_waitcnt vmcnt(0)
	v_pk_mul_f32 v[106:107], v[96:97], v[100:101] op_sel:[1,1] op_sel_hi:[0,1]
	v_mul_f32_e32 v108, v99, v103
	v_mul_f32_e32 v114, v98, v103
	v_pk_mul_f32 v[104:105], v[96:97], v[100:101]
	v_pk_fma_f32 v[96:97], v[96:97], v[100:101], v[106:107] op_sel_hi:[1,0,1]
	v_pk_fma_f32 v[100:101], v[98:99], v[102:103], v[108:109] op_sel_hi:[1,1,0] neg_lo:[0,0,1] neg_hi:[0,0,1]
	v_pk_fma_f32 v[102:103], v[98:99], v[102:103], v[114:115] op_sel:[1,0,0] op_sel_hi:[0,1,0]
	v_sub_f32_e32 v96, v104, v106
	v_mov_b32_e32 v98, v100
	v_mov_b32_e32 v99, v102
.LBB0_361:
	s_or_b64 exec, exec, s[36:37]
	v_cvt_pk_bf16_f32 v250, v96, v97
	v_cvt_pk_bf16_f32 v251, v98, v99
	v_or_b32_e32 v98, 32, v144
	v_ashrrev_i32_e32 v99, 31, v98
	s_nop 1
	v_permlane16_swap_b32_e32 v248, v250
	v_permlane16_swap_b32_e32 v249, v251
	v_lshl_add_u64 v[242:243], v[110:111], 0, v[252:253]
	global_store_dwordx4 v[242:243], v[248:251], off offset:256 sc0 sc1
	v_lshl_add_u64 v[96:97], v[98:99], 2, s[66:67]
	v_mov_b32_e32 v96, v235
	v_lshlrev_b64 v[102:103], 8, v[98:99]
	v_mul_f32_e32 v96, 0x3dd53b94, v96
	v_pk_mul_f32 v[100:101], v[94:95], v[96:97] op_sel_hi:[1,0]
	v_pk_mul_f32 v[94:95], v[92:93], v[96:97] op_sel_hi:[1,0]
	v_lshl_add_u64 v[92:93], s[16:17], 0, v[102:103]
	s_and_saveexec_b64 s[36:37], vcc
	s_cbranch_execz .LBB0_363
	v_lshl_add_u64 v[102:103], v[132:133], 3, v[92:93]
	global_load_dwordx4 v[102:105], v[102:103], off
	s_waitcnt vmcnt(0)
	v_pk_mul_f32 v[108:109], v[94:95], v[102:103] op_sel:[1,1] op_sel_hi:[0,1]
	v_mul_f32_e32 v110, v101, v105
	v_mul_f32_e32 v114, v100, v105
	v_pk_mul_f32 v[106:107], v[94:95], v[102:103]
	v_pk_fma_f32 v[94:95], v[94:95], v[102:103], v[108:109] op_sel_hi:[1,0,1]
	v_pk_fma_f32 v[102:103], v[100:101], v[104:105], v[110:111] op_sel_hi:[1,1,0] neg_lo:[0,0,1] neg_hi:[0,0,1]
	v_pk_fma_f32 v[104:105], v[100:101], v[104:105], v[114:115] op_sel:[1,0,0] op_sel_hi:[0,1,0]
	v_sub_f32_e32 v94, v106, v108
	v_mov_b32_e32 v100, v102
	v_mov_b32_e32 v101, v104
.LBB0_363:
	s_or_b64 exec, exec, s[36:37]
	v_cvt_pk_bf16_f32 v244, v94, v95
	v_mov_b64_e32 v[94:95], s[64:65]
	v_mov_b32_e32 v97, v96
	v_mad_i64_i32 v[94:95], s[12:13], v98, s83, v[94:95]
	v_mov_b32_e32 v98, v96
	v_mov_b32_e32 v99, v96
	v_lshl_add_u64 v[94:95], v[142:143], 1, v[94:95]
	v_pk_mul_f32 v[90:91], v[90:91], v[98:99]
	v_pk_mul_f32 v[88:89], v[88:89], v[96:97]
	v_cvt_pk_bf16_f32 v245, v100, v101
	s_nop 0
	s_and_saveexec_b64 s[36:37], s[6:7]
	s_cbranch_execz .LBB0_365
	v_mov_b32_e32 v121, v133
	v_lshl_add_u64 v[100:101], v[120:121], 3, v[92:93]
	global_load_dwordx4 v[100:103], v[100:101], off
	s_waitcnt vmcnt(0)
	v_pk_mul_f32 v[106:107], v[88:89], v[100:101] op_sel:[1,1] op_sel_hi:[0,1]
	v_mul_f32_e32 v108, v91, v103
	v_mul_f32_e32 v110, v90, v103
	v_pk_mul_f32 v[104:105], v[88:89], v[100:101]
	v_pk_fma_f32 v[88:89], v[88:89], v[100:101], v[106:107] op_sel_hi:[1,0,1]
	v_pk_fma_f32 v[100:101], v[90:91], v[102:103], v[108:109] op_sel_hi:[1,1,0] neg_lo:[0,0,1] neg_hi:[0,0,1]
	v_pk_fma_f32 v[102:103], v[90:91], v[102:103], v[110:111] op_sel:[1,0,0] op_sel_hi:[0,1,0]
	v_sub_f32_e32 v88, v104, v106
	v_mov_b32_e32 v90, v100
	v_mov_b32_e32 v91, v102
.LBB0_365:
	s_or_b64 exec, exec, s[36:37]
	v_pk_mul_f32 v[86:87], v[86:87], v[98:99]
	v_pk_mul_f32 v[84:85], v[84:85], v[96:97]
	v_cvt_pk_bf16_f32 v246, v88, v89
	v_cvt_pk_bf16_f32 v247, v90, v91
	s_nop 1
	v_permlane16_swap_b32_e32 v244, v246
	v_permlane16_swap_b32_e32 v245, v247
	v_lshl_add_u64 v[242:243], v[94:95], 0, v[252:253]
	global_store_dwordx4 v[242:243], v[244:247], off sc0 sc1
	s_and_saveexec_b64 s[36:37], s[8:9]
	s_cbranch_execz .LBB0_367
	v_mov_b32_e32 v117, v133
	v_lshl_add_u64 v[88:89], v[116:117], 3, v[92:93]
	global_load_dwordx4 v[88:91], v[88:89], off
	s_waitcnt vmcnt(0)
	v_pk_mul_f32 v[100:101], v[84:85], v[88:89] op_sel:[1,1] op_sel_hi:[0,1]
	v_mul_f32_e32 v102, v87, v91
	v_mul_f32_e32 v104, v86, v91
	v_pk_mul_f32 v[98:99], v[84:85], v[88:89]
	v_pk_fma_f32 v[84:85], v[84:85], v[88:89], v[100:101] op_sel_hi:[1,0,1]
	v_pk_fma_f32 v[88:89], v[86:87], v[90:91], v[102:103] op_sel_hi:[1,1,0] neg_lo:[0,0,1] neg_hi:[0,0,1]
	v_pk_fma_f32 v[90:91], v[86:87], v[90:91], v[104:105] op_sel:[1,0,0] op_sel_hi:[0,1,0]
	v_sub_f32_e32 v84, v98, v100
	v_mov_b32_e32 v86, v88
	v_mov_b32_e32 v87, v90
.LBB0_367:
	s_or_b64 exec, exec, s[36:37]
	v_cvt_pk_bf16_f32 v248, v84, v85
	v_cvt_pk_bf16_f32 v249, v86, v87
	s_nop 0
	v_mov_b32_e32 v84, v96
	v_mov_b32_e32 v85, v96
	v_pk_mul_f32 v[82:83], v[82:83], v[84:85]
	v_pk_mul_f32 v[80:81], v[80:81], v[96:97]
	s_and_saveexec_b64 s[36:37], s[10:11]
	s_cbranch_execz .LBB0_369
	v_mov_b32_e32 v113, v133
	v_lshl_add_u64 v[84:85], v[112:113], 3, v[92:93]
	global_load_dwordx4 v[84:87], v[84:85], off
	s_waitcnt vmcnt(0)
	v_pk_mul_f32 v[90:91], v[80:81], v[84:85] op_sel:[1,1] op_sel_hi:[0,1]
	v_mul_f32_e32 v92, v83, v87
	v_mul_f32_e32 v96, v82, v87
	v_pk_mul_f32 v[88:89], v[80:81], v[84:85]
	v_pk_fma_f32 v[80:81], v[80:81], v[84:85], v[90:91] op_sel_hi:[1,0,1]
	v_pk_fma_f32 v[84:85], v[82:83], v[86:87], v[92:93] op_sel_hi:[1,1,0] neg_lo:[0,0,1] neg_hi:[0,0,1]
	v_pk_fma_f32 v[86:87], v[82:83], v[86:87], v[96:97] op_sel:[1,0,0] op_sel_hi:[0,1,0]
	v_sub_f32_e32 v80, v88, v90
	v_mov_b32_e32 v82, v84
	v_mov_b32_e32 v83, v86
.LBB0_369:
	s_or_b64 exec, exec, s[36:37]
	v_cvt_pk_bf16_f32 v250, v80, v81
	v_cvt_pk_bf16_f32 v251, v82, v83
	v_or_b32_e32 v82, 48, v144
	v_ashrrev_i32_e32 v83, 31, v82
	s_nop 1
	v_permlane16_swap_b32_e32 v248, v250
	v_permlane16_swap_b32_e32 v249, v251
	v_lshl_add_u64 v[242:243], v[94:95], 0, v[252:253]
	global_store_dwordx4 v[242:243], v[248:251], off offset:256 sc0 sc1
	v_lshl_add_u64 v[80:81], v[82:83], 2, s[66:67]
	v_mov_b32_e32 v80, v236
	v_lshlrev_b64 v[86:87], 8, v[82:83]
	v_mul_f32_e32 v80, 0x3dd53b94, v80
	v_pk_mul_f32 v[84:85], v[78:79], v[80:81] op_sel_hi:[1,0]
	v_pk_mul_f32 v[78:79], v[76:77], v[80:81] op_sel_hi:[1,0]
	v_lshl_add_u64 v[76:77], s[16:17], 0, v[86:87]
	s_and_saveexec_b64 s[36:37], vcc
	s_cbranch_execz .LBB0_371
	v_lshl_add_u64 v[86:87], v[132:133], 3, v[76:77]
	global_load_dwordx4 v[86:89], v[86:87], off
	s_waitcnt vmcnt(0)
	v_pk_mul_f32 v[92:93], v[78:79], v[86:87] op_sel:[1,1] op_sel_hi:[0,1]
	v_mul_f32_e32 v94, v85, v89
	v_mul_f32_e32 v96, v84, v89
	v_pk_mul_f32 v[90:91], v[78:79], v[86:87]
	v_pk_fma_f32 v[78:79], v[78:79], v[86:87], v[92:93] op_sel_hi:[1,0,1]
	v_pk_fma_f32 v[86:87], v[84:85], v[88:89], v[94:95] op_sel_hi:[1,1,0] neg_lo:[0,0,1] neg_hi:[0,0,1]
	v_pk_fma_f32 v[88:89], v[84:85], v[88:89], v[96:97] op_sel:[1,0,0] op_sel_hi:[0,1,0]
	v_sub_f32_e32 v78, v90, v92
	v_mov_b32_e32 v84, v86
	v_mov_b32_e32 v85, v88
.LBB0_371:
	s_or_b64 exec, exec, s[36:37]
	v_cvt_pk_bf16_f32 v244, v78, v79
	v_mov_b64_e32 v[78:79], s[64:65]
	v_mov_b32_e32 v81, v80
	v_mad_i64_i32 v[78:79], s[12:13], v82, s83, v[78:79]
	v_mov_b32_e32 v82, v80
	v_mov_b32_e32 v83, v80
	v_lshl_add_u64 v[78:79], v[142:143], 1, v[78:79]
	v_pk_mul_f32 v[74:75], v[74:75], v[82:83]
	v_pk_mul_f32 v[72:73], v[72:73], v[80:81]
	v_cvt_pk_bf16_f32 v245, v84, v85
	s_nop 0
	s_and_saveexec_b64 s[36:37], s[6:7]
	s_cbranch_execz .LBB0_373
	v_mov_b32_e32 v121, v133
	v_lshl_add_u64 v[84:85], v[120:121], 3, v[76:77]
	global_load_dwordx4 v[84:87], v[84:85], off
	s_waitcnt vmcnt(0)
	v_pk_mul_f32 v[90:91], v[72:73], v[84:85] op_sel:[1,1] op_sel_hi:[0,1]
	v_mul_f32_e32 v92, v75, v87
	v_mul_f32_e32 v94, v74, v87
	v_pk_mul_f32 v[88:89], v[72:73], v[84:85]
	v_pk_fma_f32 v[72:73], v[72:73], v[84:85], v[90:91] op_sel_hi:[1,0,1]
	v_pk_fma_f32 v[84:85], v[74:75], v[86:87], v[92:93] op_sel_hi:[1,1,0] neg_lo:[0,0,1] neg_hi:[0,0,1]
	v_pk_fma_f32 v[86:87], v[74:75], v[86:87], v[94:95] op_sel:[1,0,0] op_sel_hi:[0,1,0]
	v_sub_f32_e32 v72, v88, v90
	v_mov_b32_e32 v74, v84
	v_mov_b32_e32 v75, v86
.LBB0_373:
	s_or_b64 exec, exec, s[36:37]
	v_pk_mul_f32 v[70:71], v[70:71], v[82:83]
	v_pk_mul_f32 v[68:69], v[68:69], v[80:81]
	v_cvt_pk_bf16_f32 v246, v72, v73
	v_cvt_pk_bf16_f32 v247, v74, v75
	s_nop 1
	v_permlane16_swap_b32_e32 v244, v246
	v_permlane16_swap_b32_e32 v245, v247
	v_lshl_add_u64 v[242:243], v[78:79], 0, v[252:253]
	global_store_dwordx4 v[242:243], v[244:247], off sc0 sc1
	s_and_saveexec_b64 s[36:37], s[8:9]
	s_cbranch_execz .LBB0_375
	v_mov_b32_e32 v117, v133
	v_lshl_add_u64 v[72:73], v[116:117], 3, v[76:77]
	global_load_dwordx4 v[72:75], v[72:73], off
	s_waitcnt vmcnt(0)
	v_pk_mul_f32 v[84:85], v[68:69], v[72:73] op_sel:[1,1] op_sel_hi:[0,1]
	v_mul_f32_e32 v86, v71, v75
	v_mul_f32_e32 v88, v70, v75
	v_pk_mul_f32 v[82:83], v[68:69], v[72:73]
	v_pk_fma_f32 v[68:69], v[68:69], v[72:73], v[84:85] op_sel_hi:[1,0,1]
	v_pk_fma_f32 v[72:73], v[70:71], v[74:75], v[86:87] op_sel_hi:[1,1,0] neg_lo:[0,0,1] neg_hi:[0,0,1]
	v_pk_fma_f32 v[74:75], v[70:71], v[74:75], v[88:89] op_sel:[1,0,0] op_sel_hi:[0,1,0]
	v_sub_f32_e32 v68, v82, v84
	v_mov_b32_e32 v70, v72
	v_mov_b32_e32 v71, v74
.LBB0_375:
	s_or_b64 exec, exec, s[36:37]
	v_cvt_pk_bf16_f32 v248, v68, v69
	v_cvt_pk_bf16_f32 v249, v70, v71
	s_nop 0
	v_mov_b32_e32 v68, v80
	v_mov_b32_e32 v69, v80
	v_pk_mul_f32 v[66:67], v[66:67], v[68:69]
	v_pk_mul_f32 v[64:65], v[64:65], v[80:81]
	s_and_saveexec_b64 s[36:37], s[10:11]
	s_cbranch_execz .LBB0_377
	v_mov_b32_e32 v113, v133
	v_lshl_add_u64 v[68:69], v[112:113], 3, v[76:77]
	global_load_dwordx4 v[68:71], v[68:69], off
	s_waitcnt vmcnt(0)
	v_pk_mul_f32 v[74:75], v[64:65], v[68:69] op_sel:[1,1] op_sel_hi:[0,1]
	v_mul_f32_e32 v76, v67, v71
	v_mul_f32_e32 v80, v66, v71
	v_pk_mul_f32 v[72:73], v[64:65], v[68:69]
	v_pk_fma_f32 v[64:65], v[64:65], v[68:69], v[74:75] op_sel_hi:[1,0,1]
	v_pk_fma_f32 v[68:69], v[66:67], v[70:71], v[76:77] op_sel_hi:[1,1,0] neg_lo:[0,0,1] neg_hi:[0,0,1]
	v_pk_fma_f32 v[70:71], v[66:67], v[70:71], v[80:81] op_sel:[1,0,0] op_sel_hi:[0,1,0]
	v_sub_f32_e32 v64, v72, v74
	v_mov_b32_e32 v66, v68
	v_mov_b32_e32 v67, v70
.LBB0_377:
	s_or_b64 exec, exec, s[36:37]
	v_cvt_pk_bf16_f32 v250, v64, v65
	v_cvt_pk_bf16_f32 v251, v66, v67
	v_add_u32_e32 v66, 0x80, v144
	v_ashrrev_i32_e32 v67, 31, v66
	s_nop 1
	v_permlane16_swap_b32_e32 v248, v250
	v_permlane16_swap_b32_e32 v249, v251
	v_lshl_add_u64 v[242:243], v[78:79], 0, v[252:253]
	global_store_dwordx4 v[242:243], v[248:251], off offset:256 sc0 sc1
	v_lshl_add_u64 v[64:65], v[66:67], 2, s[66:67]
	v_mov_b32_e32 v64, v237
	v_lshlrev_b64 v[70:71], 8, v[66:67]
	v_mul_f32_e32 v64, 0x3dd53b94, v64
	v_pk_mul_f32 v[68:69], v[62:63], v[64:65] op_sel_hi:[1,0]
	v_pk_mul_f32 v[62:63], v[60:61], v[64:65] op_sel_hi:[1,0]
	v_lshl_add_u64 v[60:61], s[16:17], 0, v[70:71]
	s_and_saveexec_b64 s[36:37], vcc
	s_cbranch_execz .LBB0_379
	v_lshl_add_u64 v[70:71], v[132:133], 3, v[60:61]
	global_load_dwordx4 v[70:73], v[70:71], off
	s_waitcnt vmcnt(0)
	v_pk_mul_f32 v[76:77], v[62:63], v[70:71] op_sel:[1,1] op_sel_hi:[0,1]
	v_mul_f32_e32 v78, v69, v73
	v_mul_f32_e32 v80, v68, v73
	v_pk_mul_f32 v[74:75], v[62:63], v[70:71]
	v_pk_fma_f32 v[62:63], v[62:63], v[70:71], v[76:77] op_sel_hi:[1,0,1]
	v_pk_fma_f32 v[70:71], v[68:69], v[72:73], v[78:79] op_sel_hi:[1,1,0] neg_lo:[0,0,1] neg_hi:[0,0,1]
	v_pk_fma_f32 v[72:73], v[68:69], v[72:73], v[80:81] op_sel:[1,0,0] op_sel_hi:[0,1,0]
	v_sub_f32_e32 v62, v74, v76
	v_mov_b32_e32 v68, v70
	v_mov_b32_e32 v69, v72
.LBB0_379:
	s_or_b64 exec, exec, s[36:37]
	v_cvt_pk_bf16_f32 v244, v62, v63
	v_mov_b64_e32 v[62:63], s[64:65]
	v_mov_b32_e32 v65, v64
	v_mad_i64_i32 v[62:63], s[12:13], v66, s83, v[62:63]
	v_mov_b32_e32 v66, v64
	v_mov_b32_e32 v67, v64
	v_lshl_add_u64 v[62:63], v[142:143], 1, v[62:63]
	v_pk_mul_f32 v[58:59], v[58:59], v[66:67]
	v_pk_mul_f32 v[56:57], v[56:57], v[64:65]
	v_cvt_pk_bf16_f32 v245, v68, v69
	s_nop 0
	s_and_saveexec_b64 s[36:37], s[6:7]
	s_cbranch_execz .LBB0_381
	v_mov_b32_e32 v121, v133
	v_lshl_add_u64 v[68:69], v[120:121], 3, v[60:61]
	global_load_dwordx4 v[68:71], v[68:69], off
	s_waitcnt vmcnt(0)
	v_pk_mul_f32 v[74:75], v[56:57], v[68:69] op_sel:[1,1] op_sel_hi:[0,1]
	v_mul_f32_e32 v76, v59, v71
	v_mul_f32_e32 v78, v58, v71
	v_pk_mul_f32 v[72:73], v[56:57], v[68:69]
	v_pk_fma_f32 v[56:57], v[56:57], v[68:69], v[74:75] op_sel_hi:[1,0,1]
	v_pk_fma_f32 v[68:69], v[58:59], v[70:71], v[76:77] op_sel_hi:[1,1,0] neg_lo:[0,0,1] neg_hi:[0,0,1]
	v_pk_fma_f32 v[70:71], v[58:59], v[70:71], v[78:79] op_sel:[1,0,0] op_sel_hi:[0,1,0]
	v_sub_f32_e32 v56, v72, v74
	v_mov_b32_e32 v58, v68
	v_mov_b32_e32 v59, v70
.LBB0_381:
	s_or_b64 exec, exec, s[36:37]
	v_pk_mul_f32 v[54:55], v[54:55], v[66:67]
	v_pk_mul_f32 v[52:53], v[52:53], v[64:65]
	v_cvt_pk_bf16_f32 v246, v56, v57
	v_cvt_pk_bf16_f32 v247, v58, v59
	s_nop 1
	v_permlane16_swap_b32_e32 v244, v246
	v_permlane16_swap_b32_e32 v245, v247
	v_lshl_add_u64 v[242:243], v[62:63], 0, v[252:253]
	global_store_dwordx4 v[242:243], v[244:247], off sc0 sc1
	s_and_saveexec_b64 s[36:37], s[8:9]
	s_cbranch_execz .LBB0_383
	v_mov_b32_e32 v117, v133
	v_lshl_add_u64 v[56:57], v[116:117], 3, v[60:61]
	global_load_dwordx4 v[56:59], v[56:57], off
	s_waitcnt vmcnt(0)
	v_pk_mul_f32 v[68:69], v[52:53], v[56:57] op_sel:[1,1] op_sel_hi:[0,1]
	v_mul_f32_e32 v70, v55, v59
	v_mul_f32_e32 v72, v54, v59
	v_pk_mul_f32 v[66:67], v[52:53], v[56:57]
	v_pk_fma_f32 v[52:53], v[52:53], v[56:57], v[68:69] op_sel_hi:[1,0,1]
	v_pk_fma_f32 v[56:57], v[54:55], v[58:59], v[70:71] op_sel_hi:[1,1,0] neg_lo:[0,0,1] neg_hi:[0,0,1]
	v_pk_fma_f32 v[58:59], v[54:55], v[58:59], v[72:73] op_sel:[1,0,0] op_sel_hi:[0,1,0]
	v_sub_f32_e32 v52, v66, v68
	v_mov_b32_e32 v54, v56
	v_mov_b32_e32 v55, v58
.LBB0_383:
	s_or_b64 exec, exec, s[36:37]
	v_cvt_pk_bf16_f32 v248, v52, v53
	v_cvt_pk_bf16_f32 v249, v54, v55
	s_nop 0
	v_mov_b32_e32 v52, v64
	v_mov_b32_e32 v53, v64
	v_pk_mul_f32 v[50:51], v[50:51], v[52:53]
	v_pk_mul_f32 v[48:49], v[48:49], v[64:65]
	s_and_saveexec_b64 s[36:37], s[10:11]
	s_cbranch_execz .LBB0_385
	v_mov_b32_e32 v113, v133
	v_lshl_add_u64 v[52:53], v[112:113], 3, v[60:61]
	global_load_dwordx4 v[52:55], v[52:53], off
	s_waitcnt vmcnt(0)
	v_pk_mul_f32 v[58:59], v[48:49], v[52:53] op_sel:[1,1] op_sel_hi:[0,1]
	v_mul_f32_e32 v60, v51, v55
	v_mul_f32_e32 v64, v50, v55
	v_pk_mul_f32 v[56:57], v[48:49], v[52:53]
	v_pk_fma_f32 v[48:49], v[48:49], v[52:53], v[58:59] op_sel_hi:[1,0,1]
	v_pk_fma_f32 v[52:53], v[50:51], v[54:55], v[60:61] op_sel_hi:[1,1,0] neg_lo:[0,0,1] neg_hi:[0,0,1]
	v_pk_fma_f32 v[54:55], v[50:51], v[54:55], v[64:65] op_sel:[1,0,0] op_sel_hi:[0,1,0]
	v_sub_f32_e32 v48, v56, v58
	v_mov_b32_e32 v50, v52
	v_mov_b32_e32 v51, v54
.LBB0_385:
	s_or_b64 exec, exec, s[36:37]
	v_cvt_pk_bf16_f32 v250, v48, v49
	v_cvt_pk_bf16_f32 v251, v50, v51
	v_add_u32_e32 v50, 0x90, v144
	v_ashrrev_i32_e32 v51, 31, v50
	s_nop 1
	v_permlane16_swap_b32_e32 v248, v250
	v_permlane16_swap_b32_e32 v249, v251
	v_lshl_add_u64 v[242:243], v[62:63], 0, v[252:253]
	global_store_dwordx4 v[242:243], v[248:251], off offset:256 sc0 sc1
	v_lshl_add_u64 v[48:49], v[50:51], 2, s[66:67]
	v_mov_b32_e32 v48, v238
	v_lshlrev_b64 v[54:55], 8, v[50:51]
	v_mul_f32_e32 v48, 0x3dd53b94, v48
	v_pk_mul_f32 v[52:53], v[46:47], v[48:49] op_sel_hi:[1,0]
	v_pk_mul_f32 v[46:47], v[44:45], v[48:49] op_sel_hi:[1,0]
	v_lshl_add_u64 v[44:45], s[16:17], 0, v[54:55]
	s_and_saveexec_b64 s[36:37], vcc
	s_cbranch_execz .LBB0_387
	v_lshl_add_u64 v[54:55], v[132:133], 3, v[44:45]
	global_load_dwordx4 v[54:57], v[54:55], off
	s_waitcnt vmcnt(0)
	v_pk_mul_f32 v[60:61], v[46:47], v[54:55] op_sel:[1,1] op_sel_hi:[0,1]
	v_mul_f32_e32 v62, v53, v57
	v_mul_f32_e32 v64, v52, v57
	v_pk_mul_f32 v[58:59], v[46:47], v[54:55]
	v_pk_fma_f32 v[46:47], v[46:47], v[54:55], v[60:61] op_sel_hi:[1,0,1]
	v_pk_fma_f32 v[54:55], v[52:53], v[56:57], v[62:63] op_sel_hi:[1,1,0] neg_lo:[0,0,1] neg_hi:[0,0,1]
	v_pk_fma_f32 v[56:57], v[52:53], v[56:57], v[64:65] op_sel:[1,0,0] op_sel_hi:[0,1,0]
	v_sub_f32_e32 v46, v58, v60
	v_mov_b32_e32 v52, v54
	v_mov_b32_e32 v53, v56
.LBB0_387:
	s_or_b64 exec, exec, s[36:37]
	v_cvt_pk_bf16_f32 v244, v46, v47
	v_mov_b64_e32 v[46:47], s[64:65]
	v_mov_b32_e32 v49, v48
	v_mad_i64_i32 v[46:47], s[12:13], v50, s83, v[46:47]
	v_mov_b32_e32 v50, v48
	v_mov_b32_e32 v51, v48
	v_lshl_add_u64 v[46:47], v[142:143], 1, v[46:47]
	v_pk_mul_f32 v[42:43], v[42:43], v[50:51]
	v_pk_mul_f32 v[40:41], v[40:41], v[48:49]
	v_cvt_pk_bf16_f32 v245, v52, v53
	s_nop 0
	s_and_saveexec_b64 s[36:37], s[6:7]
	s_cbranch_execz .LBB0_389
	v_mov_b32_e32 v121, v133
	v_lshl_add_u64 v[52:53], v[120:121], 3, v[44:45]
	global_load_dwordx4 v[52:55], v[52:53], off
	s_waitcnt vmcnt(0)
	v_pk_mul_f32 v[58:59], v[40:41], v[52:53] op_sel:[1,1] op_sel_hi:[0,1]
	v_mul_f32_e32 v60, v43, v55
	v_mul_f32_e32 v62, v42, v55
	v_pk_mul_f32 v[56:57], v[40:41], v[52:53]
	v_pk_fma_f32 v[40:41], v[40:41], v[52:53], v[58:59] op_sel_hi:[1,0,1]
	v_pk_fma_f32 v[52:53], v[42:43], v[54:55], v[60:61] op_sel_hi:[1,1,0] neg_lo:[0,0,1] neg_hi:[0,0,1]
	v_pk_fma_f32 v[54:55], v[42:43], v[54:55], v[62:63] op_sel:[1,0,0] op_sel_hi:[0,1,0]
	v_sub_f32_e32 v40, v56, v58
	v_mov_b32_e32 v42, v52
	v_mov_b32_e32 v43, v54
.LBB0_389:
	s_or_b64 exec, exec, s[36:37]
	v_pk_mul_f32 v[38:39], v[38:39], v[50:51]
	v_pk_mul_f32 v[36:37], v[36:37], v[48:49]
	v_cvt_pk_bf16_f32 v246, v40, v41
	v_cvt_pk_bf16_f32 v247, v42, v43
	s_nop 1
	v_permlane16_swap_b32_e32 v244, v246
	v_permlane16_swap_b32_e32 v245, v247
	v_lshl_add_u64 v[242:243], v[46:47], 0, v[252:253]
	global_store_dwordx4 v[242:243], v[244:247], off sc0 sc1
	s_and_saveexec_b64 s[36:37], s[8:9]
	s_cbranch_execz .LBB0_391
	v_mov_b32_e32 v117, v133
	v_lshl_add_u64 v[40:41], v[116:117], 3, v[44:45]
	global_load_dwordx4 v[40:43], v[40:41], off
	s_waitcnt vmcnt(0)
	v_pk_mul_f32 v[52:53], v[36:37], v[40:41] op_sel:[1,1] op_sel_hi:[0,1]
	v_mul_f32_e32 v54, v39, v43
	v_mul_f32_e32 v56, v38, v43
	v_pk_mul_f32 v[50:51], v[36:37], v[40:41]
	v_pk_fma_f32 v[36:37], v[36:37], v[40:41], v[52:53] op_sel_hi:[1,0,1]
	v_pk_fma_f32 v[40:41], v[38:39], v[42:43], v[54:55] op_sel_hi:[1,1,0] neg_lo:[0,0,1] neg_hi:[0,0,1]
	v_pk_fma_f32 v[42:43], v[38:39], v[42:43], v[56:57] op_sel:[1,0,0] op_sel_hi:[0,1,0]
	v_sub_f32_e32 v36, v50, v52
	v_mov_b32_e32 v38, v40
	v_mov_b32_e32 v39, v42
.LBB0_391:
	s_or_b64 exec, exec, s[36:37]
	v_cvt_pk_bf16_f32 v248, v36, v37
	v_cvt_pk_bf16_f32 v249, v38, v39
	s_nop 0
	v_mov_b32_e32 v36, v48
	v_mov_b32_e32 v37, v48
	v_pk_mul_f32 v[34:35], v[34:35], v[36:37]
	v_pk_mul_f32 v[32:33], v[32:33], v[48:49]
	s_and_saveexec_b64 s[36:37], s[10:11]
	s_cbranch_execz .LBB0_393
	v_mov_b32_e32 v113, v133
	v_lshl_add_u64 v[36:37], v[112:113], 3, v[44:45]
	global_load_dwordx4 v[36:39], v[36:37], off
	s_waitcnt vmcnt(0)
	v_pk_mul_f32 v[42:43], v[32:33], v[36:37] op_sel:[1,1] op_sel_hi:[0,1]
	v_mul_f32_e32 v44, v35, v39
	v_mul_f32_e32 v48, v34, v39
	v_pk_mul_f32 v[40:41], v[32:33], v[36:37]
	v_pk_fma_f32 v[32:33], v[32:33], v[36:37], v[42:43] op_sel_hi:[1,0,1]
	v_pk_fma_f32 v[36:37], v[34:35], v[38:39], v[44:45] op_sel_hi:[1,1,0] neg_lo:[0,0,1] neg_hi:[0,0,1]
	v_pk_fma_f32 v[38:39], v[34:35], v[38:39], v[48:49] op_sel:[1,0,0] op_sel_hi:[0,1,0]
	v_sub_f32_e32 v32, v40, v42
	v_mov_b32_e32 v34, v36
	v_mov_b32_e32 v35, v38
.LBB0_393:
	s_or_b64 exec, exec, s[36:37]
	v_cvt_pk_bf16_f32 v250, v32, v33
	v_cvt_pk_bf16_f32 v251, v34, v35
	v_add_u32_e32 v34, 0xa0, v144
	v_ashrrev_i32_e32 v35, 31, v34
	s_nop 1
	v_permlane16_swap_b32_e32 v248, v250
	v_permlane16_swap_b32_e32 v249, v251
	v_lshl_add_u64 v[242:243], v[46:47], 0, v[252:253]
	global_store_dwordx4 v[242:243], v[248:251], off offset:256 sc0 sc1
	v_lshl_add_u64 v[32:33], v[34:35], 2, s[66:67]
	v_mov_b32_e32 v32, v239
	v_lshlrev_b64 v[38:39], 8, v[34:35]
	v_mul_f32_e32 v32, 0x3dd53b94, v32
	v_pk_mul_f32 v[36:37], v[30:31], v[32:33] op_sel_hi:[1,0]
	v_pk_mul_f32 v[30:31], v[28:29], v[32:33] op_sel_hi:[1,0]
	v_lshl_add_u64 v[28:29], s[16:17], 0, v[38:39]
	s_and_saveexec_b64 s[36:37], vcc
	s_cbranch_execz .LBB0_395
	v_lshl_add_u64 v[38:39], v[132:133], 3, v[28:29]
	global_load_dwordx4 v[38:41], v[38:39], off
	s_waitcnt vmcnt(0)
	v_pk_mul_f32 v[44:45], v[30:31], v[38:39] op_sel:[1,1] op_sel_hi:[0,1]
	v_mul_f32_e32 v46, v37, v41
	v_mul_f32_e32 v48, v36, v41
	v_pk_mul_f32 v[42:43], v[30:31], v[38:39]
	v_pk_fma_f32 v[30:31], v[30:31], v[38:39], v[44:45] op_sel_hi:[1,0,1]
	v_pk_fma_f32 v[38:39], v[36:37], v[40:41], v[46:47] op_sel_hi:[1,1,0] neg_lo:[0,0,1] neg_hi:[0,0,1]
	v_pk_fma_f32 v[40:41], v[36:37], v[40:41], v[48:49] op_sel:[1,0,0] op_sel_hi:[0,1,0]
	v_sub_f32_e32 v30, v42, v44
	v_mov_b32_e32 v36, v38
	v_mov_b32_e32 v37, v40
.LBB0_395:
	s_or_b64 exec, exec, s[36:37]
	v_cvt_pk_bf16_f32 v244, v30, v31
	v_mov_b64_e32 v[30:31], s[64:65]
	v_mov_b32_e32 v33, v32
	v_mad_i64_i32 v[30:31], s[12:13], v34, s83, v[30:31]
	v_mov_b32_e32 v34, v32
	v_mov_b32_e32 v35, v32
	v_lshl_add_u64 v[30:31], v[142:143], 1, v[30:31]
	v_pk_mul_f32 v[26:27], v[26:27], v[34:35]
	v_pk_mul_f32 v[24:25], v[24:25], v[32:33]
	v_cvt_pk_bf16_f32 v245, v36, v37
	s_nop 0
	s_and_saveexec_b64 s[36:37], s[6:7]
	s_cbranch_execz .LBB0_397
	v_mov_b32_e32 v121, v133
	v_lshl_add_u64 v[36:37], v[120:121], 3, v[28:29]
	global_load_dwordx4 v[36:39], v[36:37], off
	s_waitcnt vmcnt(0)
	v_pk_mul_f32 v[42:43], v[24:25], v[36:37] op_sel:[1,1] op_sel_hi:[0,1]
	v_mul_f32_e32 v44, v27, v39
	v_mul_f32_e32 v46, v26, v39
	v_pk_mul_f32 v[40:41], v[24:25], v[36:37]
	v_pk_fma_f32 v[24:25], v[24:25], v[36:37], v[42:43] op_sel_hi:[1,0,1]
	v_pk_fma_f32 v[36:37], v[26:27], v[38:39], v[44:45] op_sel_hi:[1,1,0] neg_lo:[0,0,1] neg_hi:[0,0,1]
	v_pk_fma_f32 v[38:39], v[26:27], v[38:39], v[46:47] op_sel:[1,0,0] op_sel_hi:[0,1,0]
	v_sub_f32_e32 v24, v40, v42
	v_mov_b32_e32 v26, v36
	v_mov_b32_e32 v27, v38
.LBB0_397:
	s_or_b64 exec, exec, s[36:37]
	v_pk_mul_f32 v[22:23], v[22:23], v[34:35]
	v_pk_mul_f32 v[20:21], v[20:21], v[32:33]
	v_cvt_pk_bf16_f32 v246, v24, v25
	v_cvt_pk_bf16_f32 v247, v26, v27
	s_nop 1
	v_permlane16_swap_b32_e32 v244, v246
	v_permlane16_swap_b32_e32 v245, v247
	v_lshl_add_u64 v[242:243], v[30:31], 0, v[252:253]
	global_store_dwordx4 v[242:243], v[244:247], off sc0 sc1
	s_and_saveexec_b64 s[36:37], s[8:9]
	s_cbranch_execz .LBB0_399
	v_mov_b32_e32 v117, v133
	v_lshl_add_u64 v[24:25], v[116:117], 3, v[28:29]
	global_load_dwordx4 v[24:27], v[24:25], off
	s_waitcnt vmcnt(0)
	v_pk_mul_f32 v[36:37], v[20:21], v[24:25] op_sel:[1,1] op_sel_hi:[0,1]
	v_mul_f32_e32 v38, v23, v27
	v_mul_f32_e32 v40, v22, v27
	v_pk_mul_f32 v[34:35], v[20:21], v[24:25]
	v_pk_fma_f32 v[20:21], v[20:21], v[24:25], v[36:37] op_sel_hi:[1,0,1]
	v_pk_fma_f32 v[24:25], v[22:23], v[26:27], v[38:39] op_sel_hi:[1,1,0] neg_lo:[0,0,1] neg_hi:[0,0,1]
	v_pk_fma_f32 v[26:27], v[22:23], v[26:27], v[40:41] op_sel:[1,0,0] op_sel_hi:[0,1,0]
	v_sub_f32_e32 v20, v34, v36
	v_mov_b32_e32 v22, v24
	v_mov_b32_e32 v23, v26
.LBB0_399:
	s_or_b64 exec, exec, s[36:37]
	v_cvt_pk_bf16_f32 v248, v20, v21
	v_cvt_pk_bf16_f32 v249, v22, v23
	s_nop 0
	v_mov_b32_e32 v20, v32
	v_mov_b32_e32 v21, v32
	v_pk_mul_f32 v[18:19], v[18:19], v[20:21]
	v_pk_mul_f32 v[16:17], v[16:17], v[32:33]
	s_and_saveexec_b64 s[36:37], s[10:11]
	s_cbranch_execz .LBB0_401
	v_mov_b32_e32 v113, v133
	v_lshl_add_u64 v[20:21], v[112:113], 3, v[28:29]
	global_load_dwordx4 v[20:23], v[20:21], off
	s_waitcnt vmcnt(0)
	v_pk_mul_f32 v[26:27], v[16:17], v[20:21] op_sel:[1,1] op_sel_hi:[0,1]
	v_mul_f32_e32 v28, v19, v23
	v_mul_f32_e32 v32, v18, v23
	v_pk_mul_f32 v[24:25], v[16:17], v[20:21]
	v_pk_fma_f32 v[16:17], v[16:17], v[20:21], v[26:27] op_sel_hi:[1,0,1]
	v_pk_fma_f32 v[20:21], v[18:19], v[22:23], v[28:29] op_sel_hi:[1,1,0] neg_lo:[0,0,1] neg_hi:[0,0,1]
	v_pk_fma_f32 v[22:23], v[18:19], v[22:23], v[32:33] op_sel:[1,0,0] op_sel_hi:[0,1,0]
	v_sub_f32_e32 v16, v24, v26
	v_mov_b32_e32 v18, v20
	v_mov_b32_e32 v19, v22
.LBB0_401:
	s_or_b64 exec, exec, s[36:37]
	v_cvt_pk_bf16_f32 v250, v16, v17
	v_cvt_pk_bf16_f32 v251, v18, v19
	v_add_u32_e32 v18, 0xb0, v144
	v_ashrrev_i32_e32 v19, 31, v18
	s_nop 1
	v_permlane16_swap_b32_e32 v248, v250
	v_permlane16_swap_b32_e32 v249, v251
	v_lshl_add_u64 v[242:243], v[30:31], 0, v[252:253]
	global_store_dwordx4 v[242:243], v[248:251], off offset:256 sc0 sc1
	v_lshl_add_u64 v[16:17], v[18:19], 2, s[66:67]
	v_mov_b32_e32 v16, v240
	v_lshlrev_b64 v[22:23], 8, v[18:19]
	v_mul_f32_e32 v16, 0x3dd53b94, v16
	v_pk_mul_f32 v[20:21], v[14:15], v[16:17] op_sel_hi:[1,0]
	v_pk_mul_f32 v[14:15], v[12:13], v[16:17] op_sel_hi:[1,0]
	v_lshl_add_u64 v[12:13], s[16:17], 0, v[22:23]
	s_and_saveexec_b64 s[36:37], vcc
	s_cbranch_execz .LBB0_403
	v_lshl_add_u64 v[22:23], v[132:133], 3, v[12:13]
	global_load_dwordx4 v[22:25], v[22:23], off
	s_waitcnt vmcnt(0)
	v_pk_mul_f32 v[28:29], v[14:15], v[22:23] op_sel:[1,1] op_sel_hi:[0,1]
	v_mul_f32_e32 v30, v21, v25
	v_mul_f32_e32 v32, v20, v25
	v_pk_mul_f32 v[26:27], v[14:15], v[22:23]
	v_pk_fma_f32 v[14:15], v[14:15], v[22:23], v[28:29] op_sel_hi:[1,0,1]
	v_pk_fma_f32 v[22:23], v[20:21], v[24:25], v[30:31] op_sel_hi:[1,1,0] neg_lo:[0,0,1] neg_hi:[0,0,1]
	v_pk_fma_f32 v[24:25], v[20:21], v[24:25], v[32:33] op_sel:[1,0,0] op_sel_hi:[0,1,0]
	v_sub_f32_e32 v14, v26, v28
	v_mov_b32_e32 v20, v22
	v_mov_b32_e32 v21, v24
.LBB0_403:
	s_or_b64 exec, exec, s[36:37]
	v_cvt_pk_bf16_f32 v244, v14, v15
	v_mov_b64_e32 v[14:15], s[64:65]
	v_mov_b32_e32 v17, v16
	v_mad_i64_i32 v[14:15], s[12:13], v18, s83, v[14:15]
	v_mov_b32_e32 v18, v16
	v_mov_b32_e32 v19, v16
	v_lshl_add_u64 v[14:15], v[142:143], 1, v[14:15]
	v_pk_mul_f32 v[10:11], v[10:11], v[18:19]
	v_pk_mul_f32 v[8:9], v[8:9], v[16:17]
	v_cvt_pk_bf16_f32 v245, v20, v21
	s_nop 0
	s_and_saveexec_b64 s[36:37], s[6:7]
	s_cbranch_execz .LBB0_405
	v_mov_b32_e32 v121, v133
	v_lshl_add_u64 v[20:21], v[120:121], 3, v[12:13]
	global_load_dwordx4 v[20:23], v[20:21], off
	s_waitcnt vmcnt(0)
	v_pk_mul_f32 v[26:27], v[8:9], v[20:21] op_sel:[1,1] op_sel_hi:[0,1]
	v_mul_f32_e32 v28, v11, v23
	v_mul_f32_e32 v30, v10, v23
	v_pk_mul_f32 v[24:25], v[8:9], v[20:21]
	v_pk_fma_f32 v[8:9], v[8:9], v[20:21], v[26:27] op_sel_hi:[1,0,1]
	v_pk_fma_f32 v[20:21], v[10:11], v[22:23], v[28:29] op_sel_hi:[1,1,0] neg_lo:[0,0,1] neg_hi:[0,0,1]
	v_pk_fma_f32 v[22:23], v[10:11], v[22:23], v[30:31] op_sel:[1,0,0] op_sel_hi:[0,1,0]
	v_sub_f32_e32 v8, v24, v26
	v_mov_b32_e32 v10, v20
	v_mov_b32_e32 v11, v22
.LBB0_405:
	s_or_b64 exec, exec, s[36:37]
	v_pk_mul_f32 v[6:7], v[6:7], v[18:19]
	v_pk_mul_f32 v[4:5], v[4:5], v[16:17]
	v_cvt_pk_bf16_f32 v246, v8, v9
	v_cvt_pk_bf16_f32 v247, v10, v11
	s_nop 1
	v_permlane16_swap_b32_e32 v244, v246
	v_permlane16_swap_b32_e32 v245, v247
	v_lshl_add_u64 v[242:243], v[14:15], 0, v[252:253]
	global_store_dwordx4 v[242:243], v[244:247], off sc0 sc1
	s_and_saveexec_b64 s[6:7], s[8:9]
	s_cbranch_execz .LBB0_407
	v_mov_b32_e32 v117, v133
	v_lshl_add_u64 v[8:9], v[116:117], 3, v[12:13]
	global_load_dwordx4 v[8:11], v[8:9], off
	s_waitcnt vmcnt(0)
	v_pk_mul_f32 v[20:21], v[4:5], v[8:9] op_sel:[1,1] op_sel_hi:[0,1]
	v_mul_f32_e32 v22, v7, v11
	v_mul_f32_e32 v24, v6, v11
	v_pk_mul_f32 v[18:19], v[4:5], v[8:9]
	v_pk_fma_f32 v[4:5], v[4:5], v[8:9], v[20:21] op_sel_hi:[1,0,1]
	v_pk_fma_f32 v[8:9], v[6:7], v[10:11], v[22:23] op_sel_hi:[1,1,0] neg_lo:[0,0,1] neg_hi:[0,0,1]
	v_pk_fma_f32 v[10:11], v[6:7], v[10:11], v[24:25] op_sel:[1,0,0] op_sel_hi:[0,1,0]
	v_sub_f32_e32 v4, v18, v20
	v_mov_b32_e32 v6, v8
	v_mov_b32_e32 v7, v10
.LBB0_407:
	s_or_b64 exec, exec, s[6:7]
	v_cvt_pk_bf16_f32 v248, v4, v5
	v_cvt_pk_bf16_f32 v249, v6, v7
	s_nop 0
	v_mov_b32_e32 v4, v16
	v_mov_b32_e32 v5, v16
	v_pk_mul_f32 v[2:3], v[2:3], v[4:5]
	v_pk_mul_f32 v[0:1], v[0:1], v[16:17]
	s_and_saveexec_b64 s[6:7], s[10:11]
	s_cbranch_execz .LBB0_409
	v_mov_b32_e32 v113, v133
	v_lshl_add_u64 v[4:5], v[112:113], 3, v[12:13]
	global_load_dwordx4 v[4:7], v[4:5], off
	s_waitcnt vmcnt(0)
	v_pk_mul_f32 v[10:11], v[0:1], v[4:5] op_sel:[1,1] op_sel_hi:[0,1]
	v_mul_f32_e32 v12, v3, v7
	v_mul_f32_e32 v16, v2, v7
	v_pk_mul_f32 v[8:9], v[0:1], v[4:5]
	v_pk_fma_f32 v[0:1], v[0:1], v[4:5], v[10:11] op_sel_hi:[1,0,1]
	v_pk_fma_f32 v[4:5], v[2:3], v[6:7], v[12:13] op_sel_hi:[1,1,0] neg_lo:[0,0,1] neg_hi:[0,0,1]
	v_pk_fma_f32 v[6:7], v[2:3], v[6:7], v[16:17] op_sel:[1,0,0] op_sel_hi:[0,1,0]
	v_sub_f32_e32 v0, v8, v10
	v_mov_b32_e32 v2, v4
	v_mov_b32_e32 v3, v6
.LBB0_409:
	s_or_b64 exec, exec, s[6:7]
	s_andn2_b64 vcc, exec, s[4:5]
	s_mov_b64 s[4:5], -1
	v_cvt_pk_bf16_f32 v250, v0, v1
	v_cvt_pk_bf16_f32 v251, v2, v3
	s_nop 1
	v_permlane16_swap_b32_e32 v248, v250
	v_permlane16_swap_b32_e32 v249, v251
	v_lshl_add_u64 v[242:243], v[14:15], 0, v[252:253]
	global_store_dwordx4 v[242:243], v[248:251], off offset:256 sc0 sc1
	s_cbranch_vccnz .LBB0_338
	s_andn2_b64 vcc, exec, s[18:19]
	s_cbranch_vccnz .LBB0_337
	s_barrier
	s_branch .LBB0_337
